# adds packed-add tree for the softmax row sums in the differential-attention loops and drops the redundant setprio 0/1 pair and lgkmcnt(0) inside each GEMM compute segment
# speedup vs baseline: 1.0149x; 1.0063x over previous
; #define PG8_STAGE(bufoff, gbase, voff) do { _Pragma("unroll") for (int _i = 0; _i < 2; ++_i) \
;         __builtin_amdgcn_global_load_lds((const unsigned*)((const char*)(gbase) + (voff)[_i]), (LAS unsigned*)(lds + (bufoff) + ldsw + _i * 8192), 16, 0, 0); } while (0)
; #define PG8_LDA(dst, b, h) do { _Pragma("unroll") for (int m = 0; m < 4; ++m) _Pragma("unroll") for (int k = 0; k < 2; ++k) dst[m][k] = *(const LAS bf16x8*)(lds + PG8_SA(b, h) + aoff + m * 2048 + k * 1024); } while (0)
; #define PG8_LDB(dst, b, h) do { _Pragma("unroll") for (int n = 0; n < 2; ++n) _Pragma("unroll") for (int k = 0; k < 2; ++k) dst[n][k] = *(const LAS bf16x8*)(lds + PG8_SB(b, h) + boff + n * 2048 + k * 1024); } while (0)
; #define PG8_MMA(ai, bj, At, Bt) do { __builtin_amdgcn_s_setprio(1); _Pragma("unroll") for (int m = 0; m < 4; ++m) _Pragma("unroll") for (int n = 0; n < 2; ++n) _Pragma("unroll") for (int k = 0; k < 2; ++k) \
;         acc[ai][bj][m][n] = __builtin_amdgcn_mfma_f32_16x16x32_bf16(Bt[n][k], At[m][k], acc[ai][bj][m][n], 0, 0, 0); __builtin_amdgcn_s_setprio(0); } while (0)
; #define PG8_WAIT_V(n) asm volatile("s_waitcnt vmcnt(" #n ")" ::: "memory")
; #define PG8_WAIT_L(n) asm volatile("s_waitcnt lgkmcnt(" #n ")" ::: "memory")
; #define PG8_BAR __builtin_amdgcn_s_barrier()
; #define PG8_SCHED __builtin_amdgcn_sched_barrier(0)
; __device__ __forceinline__ void gemm_phase(LAS unsigned char* lds, const Gemm g, const StaticOrder& S, const Epi& E) {
;     ...
;             PG8_LDB(B0, 0, 0); PG8_LDB(B1, 0, 1); PG8_SCHED; PG8_LDA(At, 0, 0); PG8_STAGE(PG8_SA(1, 1), a1 + hstepA, voffA);
;             PG8_WAIT_V(8); PG8_WAIT_L(0); PG8_BAR; PG8_MMA(0, 0, At, B0); PG8_MMA(0, 1, At, B1); PG8_BAR; PG8_SCHED;
;             PG8_LDA(At, 0, 1); PG8_STAGE(PG8_SB(0, 0), b2, voffB); PG8_STAGE(PG8_SB(0, 1), b2 + hstepB, voffB); PG8_STAGE(PG8_SA(0, 0), a2, voffA);
;             PG8_WAIT_V(8); PG8_WAIT_L(0); PG8_BAR; PG8_MMA(1, 0, At, B0); PG8_MMA(1, 1, At, B1); PG8_BAR; PG8_SCHED;
.LBB0_177:
	v_add_u32_e32 v142, s39, v177
	v_add_u32_e32 v182, s24, v177
	s_waitcnt lgkmcnt(0)
	ds_read_b128 v[130:133], v142
	ds_read_b128 v[134:137], v142 offset:1024
	ds_read_b128 v[138:141], v142 offset:2048
	ds_read_b128 v[142:145], v142 offset:3072
	ds_read_b128 v[146:149], v182
	ds_read_b128 v[150:153], v182 offset:1024
	ds_read_b128 v[154:157], v182 offset:2048
	ds_read_b128 v[182:185], v182 offset:3072
	s_add_i32 s27, s17, 2
	s_add_u32 s2, s0, 0x80
	s_addc_u32 s3, s1, 0
	s_cmp_eq_u32 s85, s17
	s_cselect_b32 s3, s7, s3
	s_cselect_b32 s2, s6, s2
	s_cselect_b32 s41, s95, s16
	s_cselect_b32 s40, s94, s5
	s_add_i32 m0, s71, 0xc000
	ds_read_b128 v[186:189], v217
	ds_read_b128 v[190:193], v217 offset:1024
	ds_read_b128 v[194:197], v217 offset:2048
	ds_read_b128 v[198:201], v217 offset:3072
	ds_read_b128 v[202:205], v217 offset:4096
	ds_read_b128 v[206:209], v217 offset:5120
	ds_read_b128 v[218:221], v217 offset:6144
	ds_read_b128 v[222:225], v217 offset:7168
	global_load_lds_dwordx4 v178, s[0:1]
	s_add_i32 m0, s71, 0xe000
	s_nop 0
	global_load_lds_dwordx4 v180, s[0:1]
	s_waitcnt vmcnt(8)
	s_waitcnt lgkmcnt(0)
	s_barrier
	s_setprio 1
	v_mfma_f32_16x16x32_bf16 v[114:117], v[130:133], v[186:189], v[114:117]
	v_mfma_f32_16x16x32_bf16 v[126:129], v[138:141], v[186:189], v[126:129]
	v_mfma_f32_16x16x32_bf16 v[110:113], v[130:133], v[194:197], v[110:113]
	v_mfma_f32_16x16x32_bf16 v[102:105], v[138:141], v[194:197], v[102:105]
	v_mfma_f32_16x16x32_bf16 v[94:97], v[130:133], v[202:205], v[94:97]
	v_mfma_f32_16x16x32_bf16 v[86:89], v[138:141], v[202:205], v[86:89]
	v_mfma_f32_16x16x32_bf16 v[78:81], v[130:133], v[218:221], v[78:81]
	v_mfma_f32_16x16x32_bf16 v[70:73], v[138:141], v[218:221], v[70:73]
	v_mfma_f32_16x16x32_bf16 v[114:117], v[134:137], v[190:193], v[114:117]
	v_mfma_f32_16x16x32_bf16 v[126:129], v[142:145], v[190:193], v[126:129]
	v_mfma_f32_16x16x32_bf16 v[110:113], v[134:137], v[198:201], v[110:113]
	v_mfma_f32_16x16x32_bf16 v[102:105], v[142:145], v[198:201], v[102:105]
	v_mfma_f32_16x16x32_bf16 v[94:97], v[134:137], v[206:209], v[94:97]
	v_mfma_f32_16x16x32_bf16 v[86:89], v[142:145], v[206:209], v[86:89]
	v_mfma_f32_16x16x32_bf16 v[78:81], v[134:137], v[222:225], v[78:81]
	v_mfma_f32_16x16x32_bf16 v[70:73], v[142:145], v[222:225], v[70:73]
	v_mfma_f32_16x16x32_bf16 v[122:125], v[146:149], v[186:189], v[122:125]
	v_mfma_f32_16x16x32_bf16 v[118:121], v[154:157], v[186:189], v[118:121]
	v_mfma_f32_16x16x32_bf16 v[106:109], v[146:149], v[194:197], v[106:109]
	v_mfma_f32_16x16x32_bf16 v[98:101], v[154:157], v[194:197], v[98:101]
	v_mfma_f32_16x16x32_bf16 v[90:93], v[146:149], v[202:205], v[90:93]
	v_mfma_f32_16x16x32_bf16 v[82:85], v[154:157], v[202:205], v[82:85]
	v_mfma_f32_16x16x32_bf16 v[74:77], v[146:149], v[218:221], v[74:77]
	v_mfma_f32_16x16x32_bf16 v[66:69], v[154:157], v[218:221], v[66:69]
	v_mfma_f32_16x16x32_bf16 v[122:125], v[150:153], v[190:193], v[122:125]
	v_mfma_f32_16x16x32_bf16 v[118:121], v[182:185], v[190:193], v[118:121]
	v_mfma_f32_16x16x32_bf16 v[106:109], v[150:153], v[198:201], v[106:109]
	v_mfma_f32_16x16x32_bf16 v[98:101], v[182:185], v[198:201], v[98:101]
	v_mfma_f32_16x16x32_bf16 v[90:93], v[150:153], v[206:209], v[90:93]
	v_mfma_f32_16x16x32_bf16 v[82:85], v[182:185], v[206:209], v[82:85]
	v_mfma_f32_16x16x32_bf16 v[74:77], v[150:153], v[222:225], v[74:77]
	v_mfma_f32_16x16x32_bf16 v[66:69], v[182:185], v[222:225], v[66:69]
	s_setprio 0
	s_barrier
	s_add_i32 s17, s39, s70
	s_mov_b32 m0, s17
	ds_read_b128 v[186:189], v217 offset:16384
	ds_read_b128 v[190:193], v217 offset:17408
	ds_read_b128 v[194:197], v217 offset:18432
	ds_read_b128 v[198:201], v217 offset:19456
	ds_read_b128 v[202:205], v217 offset:20480
	ds_read_b128 v[206:209], v217 offset:21504
	ds_read_b128 v[218:221], v217 offset:22528
	ds_read_b128 v[222:225], v217 offset:23552
	global_load_lds_dwordx4 v160, s[40:41]
	s_add_i32 m0, s17, 0x2000
	s_add_i32 s17, s24, s70
	global_load_lds_dwordx4 v164, s[40:41]
	s_add_u32 s40, s40, s52
	s_addc_u32 s41, s41, s53
	s_mov_b32 m0, s17
	s_nop 0
	global_load_lds_dwordx4 v160, s[40:41]
	s_add_i32 m0, s17, 0x2000
	s_nop 0
	global_load_lds_dwordx4 v164, s[40:41]
	s_mov_b32 m0, s71
	s_nop 0
	global_load_lds_dwordx4 v158, s[2:3]
	s_mov_b32 m0, s34
	s_nop 0
	global_load_lds_dwordx4 v162, s[2:3]
	s_waitcnt vmcnt(8)
	s_waitcnt lgkmcnt(0)
	s_barrier
	s_setprio 1
	v_mfma_f32_16x16x32_bf16 v[62:65], v[130:133], v[186:189], v[62:65]
	v_mfma_f32_16x16x32_bf16 v[54:57], v[138:141], v[186:189], v[54:57]
	v_mfma_f32_16x16x32_bf16 v[46:49], v[130:133], v[194:197], v[46:49]
	v_mfma_f32_16x16x32_bf16 v[38:41], v[138:141], v[194:197], v[38:41]
	v_mfma_f32_16x16x32_bf16 v[30:33], v[130:133], v[202:205], v[30:33]
	v_mfma_f32_16x16x32_bf16 v[22:25], v[138:141], v[202:205], v[22:25]
	v_mfma_f32_16x16x32_bf16 v[14:17], v[130:133], v[218:221], v[14:17]
	v_mfma_f32_16x16x32_bf16 v[6:9], v[138:141], v[218:221], v[6:9]
	v_mfma_f32_16x16x32_bf16 v[62:65], v[134:137], v[190:193], v[62:65]
	v_mfma_f32_16x16x32_bf16 v[54:57], v[142:145], v[190:193], v[54:57]
	v_mfma_f32_16x16x32_bf16 v[46:49], v[134:137], v[198:201], v[46:49]
	v_mfma_f32_16x16x32_bf16 v[38:41], v[142:145], v[198:201], v[38:41]
	v_mfma_f32_16x16x32_bf16 v[30:33], v[134:137], v[206:209], v[30:33]
	v_mfma_f32_16x16x32_bf16 v[22:25], v[142:145], v[206:209], v[22:25]
	v_mfma_f32_16x16x32_bf16 v[14:17], v[134:137], v[222:225], v[14:17]
	v_mfma_f32_16x16x32_bf16 v[6:9], v[142:145], v[222:225], v[6:9]
	v_mfma_f32_16x16x32_bf16 v[58:61], v[146:149], v[186:189], v[58:61]
	v_mfma_f32_16x16x32_bf16 v[50:53], v[154:157], v[186:189], v[50:53]
	v_mfma_f32_16x16x32_bf16 v[42:45], v[146:149], v[194:197], v[42:45]
	v_mfma_f32_16x16x32_bf16 v[34:37], v[154:157], v[194:197], v[34:37]
	v_mfma_f32_16x16x32_bf16 v[26:29], v[146:149], v[202:205], v[26:29]
	v_mfma_f32_16x16x32_bf16 v[18:21], v[154:157], v[202:205], v[18:21]
	v_mfma_f32_16x16x32_bf16 v[10:13], v[146:149], v[218:221], v[10:13]
	v_mfma_f32_16x16x32_bf16 v[2:5], v[154:157], v[218:221], v[2:5]
	v_mfma_f32_16x16x32_bf16 v[58:61], v[150:153], v[190:193], v[58:61]
	v_mfma_f32_16x16x32_bf16 v[50:53], v[182:185], v[190:193], v[50:53]
	v_mfma_f32_16x16x32_bf16 v[42:45], v[150:153], v[198:201], v[42:45]
	v_mfma_f32_16x16x32_bf16 v[34:37], v[182:185], v[198:201], v[34:37]
	v_mfma_f32_16x16x32_bf16 v[26:29], v[150:153], v[206:209], v[26:29]
	v_mfma_f32_16x16x32_bf16 v[18:21], v[182:185], v[206:209], v[18:21]
	v_mfma_f32_16x16x32_bf16 v[10:13], v[150:153], v[222:225], v[10:13]
	v_mfma_f32_16x16x32_bf16 v[2:5], v[182:185], v[222:225], v[2:5]
	s_setprio 0
	s_barrier
; #define PG8_STAGE(bufoff, gbase, voff) do { _Pragma("unroll") for (int _i = 0; _i < 2; ++_i) \
;         __builtin_amdgcn_global_load_lds((const unsigned*)((const char*)(gbase) + (voff)[_i]), (LAS unsigned*)(lds + (bufoff) + ldsw + _i * 8192), 16, 0, 0); } while (0)
; #define PG8_LDA(dst, b, h) do { _Pragma("unroll") for (int m = 0; m < 4; ++m) _Pragma("unroll") for (int k = 0; k < 2; ++k) dst[m][k] = *(const LAS bf16x8*)(lds + PG8_SA(b, h) + aoff + m * 2048 + k * 1024); } while (0)
; #define PG8_LDB(dst, b, h) do { _Pragma("unroll") for (int n = 0; n < 2; ++n) _Pragma("unroll") for (int k = 0; k < 2; ++k) dst[n][k] = *(const LAS bf16x8*)(lds + PG8_SB(b, h) + boff + n * 2048 + k * 1024); } while (0)
; #define PG8_MMA(ai, bj, At, Bt) do { __builtin_amdgcn_s_setprio(1); _Pragma("unroll") for (int m = 0; m < 4; ++m) _Pragma("unroll") for (int n = 0; n < 2; ++n) _Pragma("unroll") for (int k = 0; k < 2; ++k) \
;         acc[ai][bj][m][n] = __builtin_amdgcn_mfma_f32_16x16x32_bf16(Bt[n][k], At[m][k], acc[ai][bj][m][n], 0, 0, 0); __builtin_amdgcn_s_setprio(0); } while (0)
; #define PG8_WAIT_V(n) asm volatile("s_waitcnt vmcnt(" #n ")" ::: "memory")
; #define PG8_WAIT_L(n) asm volatile("s_waitcnt lgkmcnt(" #n ")" ::: "memory")
; #define PG8_BAR __builtin_amdgcn_s_barrier()
; #define PG8_SCHED __builtin_amdgcn_sched_barrier(0)
; __device__ __forceinline__ void gemm_phase(LAS unsigned char* lds, const Gemm g, const StaticOrder& S, const Epi& E) {
;     ...
;             PG8_LDB(B0, 1, 0); PG8_LDB(B1, 1, 1); PG8_SCHED; PG8_LDA(At, 1, 0); PG8_STAGE(PG8_SA(0, 1), a2 + hstepA, voffA);
;             PG8_WAIT_V(8); PG8_WAIT_L(0); PG8_BAR; PG8_MMA(0, 0, At, B0); PG8_MMA(0, 1, At, B1); PG8_BAR; PG8_SCHED;
;             PG8_LDA(At, 1, 1); PG8_STAGE(PG8_SB(1, 0), b3, voffB); PG8_STAGE(PG8_SB(1, 1), b3 + hstepB, voffB); PG8_STAGE(PG8_SA(1, 0), a3, voffA);
;             PG8_WAIT_V(8); PG8_WAIT_L(0); PG8_BAR; PG8_MMA(1, 0, At, B0); PG8_MMA(1, 1, At, B1); PG8_BAR; PG8_SCHED;
	v_add_u32_e32 v142, s25, v177
	v_add_u32_e32 v182, s26, v177
	ds_read_b128 v[130:133], v142
	ds_read_b128 v[134:137], v142 offset:1024
	ds_read_b128 v[138:141], v142 offset:2048
	ds_read_b128 v[142:145], v142 offset:3072
	ds_read_b128 v[146:149], v182
	ds_read_b128 v[150:153], v182 offset:1024
	ds_read_b128 v[154:157], v182 offset:2048
	ds_read_b128 v[182:185], v182 offset:3072
	s_add_u32 s2, s2, s50
	s_addc_u32 s3, s3, s51
	s_mov_b32 m0, s92
	ds_read_b128 v[186:189], v217 offset:32768
	ds_read_b128 v[190:193], v217 offset:33792
	ds_read_b128 v[194:197], v217 offset:34816
	ds_read_b128 v[198:201], v217 offset:35840
	ds_read_b128 v[202:205], v217 offset:36864
	ds_read_b128 v[206:209], v217 offset:37888
	ds_read_b128 v[218:221], v217 offset:38912
	ds_read_b128 v[222:225], v217 offset:39936
	global_load_lds_dwordx4 v158, s[2:3]
	s_mov_b32 m0, s93
	s_nop 0
	global_load_lds_dwordx4 v162, s[2:3]
	s_waitcnt vmcnt(8)
	s_waitcnt lgkmcnt(0)
	s_barrier
	s_setprio 1
	v_mfma_f32_16x16x32_bf16 v[114:117], v[130:133], v[186:189], v[114:117]
	v_mfma_f32_16x16x32_bf16 v[126:129], v[138:141], v[186:189], v[126:129]
	v_mfma_f32_16x16x32_bf16 v[110:113], v[130:133], v[194:197], v[110:113]
	v_mfma_f32_16x16x32_bf16 v[102:105], v[138:141], v[194:197], v[102:105]
	v_mfma_f32_16x16x32_bf16 v[94:97], v[130:133], v[202:205], v[94:97]
	v_mfma_f32_16x16x32_bf16 v[86:89], v[138:141], v[202:205], v[86:89]
	v_mfma_f32_16x16x32_bf16 v[78:81], v[130:133], v[218:221], v[78:81]
	v_mfma_f32_16x16x32_bf16 v[70:73], v[138:141], v[218:221], v[70:73]
	v_mfma_f32_16x16x32_bf16 v[114:117], v[134:137], v[190:193], v[114:117]
	v_mfma_f32_16x16x32_bf16 v[126:129], v[142:145], v[190:193], v[126:129]
	v_mfma_f32_16x16x32_bf16 v[110:113], v[134:137], v[198:201], v[110:113]
	v_mfma_f32_16x16x32_bf16 v[102:105], v[142:145], v[198:201], v[102:105]
	v_mfma_f32_16x16x32_bf16 v[94:97], v[134:137], v[206:209], v[94:97]
	v_mfma_f32_16x16x32_bf16 v[86:89], v[142:145], v[206:209], v[86:89]
	v_mfma_f32_16x16x32_bf16 v[78:81], v[134:137], v[222:225], v[78:81]
	v_mfma_f32_16x16x32_bf16 v[70:73], v[142:145], v[222:225], v[70:73]
	v_mfma_f32_16x16x32_bf16 v[122:125], v[146:149], v[186:189], v[122:125]
	v_mfma_f32_16x16x32_bf16 v[118:121], v[154:157], v[186:189], v[118:121]
	v_mfma_f32_16x16x32_bf16 v[106:109], v[146:149], v[194:197], v[106:109]
	v_mfma_f32_16x16x32_bf16 v[98:101], v[154:157], v[194:197], v[98:101]
	v_mfma_f32_16x16x32_bf16 v[90:93], v[146:149], v[202:205], v[90:93]
	v_mfma_f32_16x16x32_bf16 v[82:85], v[154:157], v[202:205], v[82:85]
	v_mfma_f32_16x16x32_bf16 v[74:77], v[146:149], v[218:221], v[74:77]
	v_mfma_f32_16x16x32_bf16 v[66:69], v[154:157], v[218:221], v[66:69]
	v_mfma_f32_16x16x32_bf16 v[122:125], v[150:153], v[190:193], v[122:125]
	v_mfma_f32_16x16x32_bf16 v[118:121], v[182:185], v[190:193], v[118:121]
	v_mfma_f32_16x16x32_bf16 v[106:109], v[150:153], v[198:201], v[106:109]
	v_mfma_f32_16x16x32_bf16 v[98:101], v[182:185], v[198:201], v[98:101]
	v_mfma_f32_16x16x32_bf16 v[90:93], v[150:153], v[206:209], v[90:93]
	v_mfma_f32_16x16x32_bf16 v[82:85], v[182:185], v[206:209], v[82:85]
	v_mfma_f32_16x16x32_bf16 v[74:77], v[150:153], v[222:225], v[74:77]
	v_mfma_f32_16x16x32_bf16 v[66:69], v[182:185], v[222:225], v[66:69]
	s_setprio 0
	s_barrier
	s_add_u32 s40, s40, 0x80
	s_addc_u32 s41, s41, 0
	s_sub_u32 s100, s40, s52
	s_subb_u32 s101, s41, s53
	s_sub_u32 s2, s2, s50
	s_subb_u32 s3, s3, s51
	s_add_u32 s2, s2, 0x80
	s_addc_u32 s3, s3, 0
	s_add_i32 vcc_lo, s25, s70
	s_mov_b32 m0, vcc_lo
	ds_read_b128 v[186:189], v217 offset:49152
	ds_read_b128 v[190:193], v217 offset:50176
	ds_read_b128 v[194:197], v217 offset:51200
	ds_read_b128 v[198:201], v217 offset:52224
	ds_read_b128 v[202:205], v217 offset:53248
	ds_read_b128 v[206:209], v217 offset:54272
	ds_read_b128 v[218:221], v217 offset:55296
	ds_read_b128 v[222:225], v217 offset:56320
	global_load_lds_dwordx4 v160, s[100:101]
	s_add_i32 m0, vcc_lo, 0x2000
	s_add_i32 vcc_lo, s26, s70
	global_load_lds_dwordx4 v164, s[100:101]
	s_mov_b32 m0, vcc_lo
	s_nop 0
	global_load_lds_dwordx4 v160, s[40:41]
	s_add_i32 m0, vcc_lo, 0x2000
	s_nop 0
	global_load_lds_dwordx4 v164, s[40:41]
	s_mov_b32 m0, s58
	s_nop 0
	global_load_lds_dwordx4 v158, s[2:3]
	s_mov_b32 m0, s59
	s_nop 0
	global_load_lds_dwordx4 v162, s[2:3]
	s_waitcnt vmcnt(8)
	s_waitcnt lgkmcnt(0)
	s_barrier
	s_setprio 1
	v_mfma_f32_16x16x32_bf16 v[62:65], v[130:133], v[186:189], v[62:65]
	v_mfma_f32_16x16x32_bf16 v[54:57], v[138:141], v[186:189], v[54:57]
	v_mfma_f32_16x16x32_bf16 v[46:49], v[130:133], v[194:197], v[46:49]
	v_mfma_f32_16x16x32_bf16 v[38:41], v[138:141], v[194:197], v[38:41]
	v_mfma_f32_16x16x32_bf16 v[30:33], v[130:133], v[202:205], v[30:33]
	v_mfma_f32_16x16x32_bf16 v[22:25], v[138:141], v[202:205], v[22:25]
	v_mfma_f32_16x16x32_bf16 v[14:17], v[130:133], v[218:221], v[14:17]
	v_mfma_f32_16x16x32_bf16 v[6:9], v[138:141], v[218:221], v[6:9]
	v_mfma_f32_16x16x32_bf16 v[62:65], v[134:137], v[190:193], v[62:65]
	v_mfma_f32_16x16x32_bf16 v[54:57], v[142:145], v[190:193], v[54:57]
	v_mfma_f32_16x16x32_bf16 v[46:49], v[134:137], v[198:201], v[46:49]
	v_mfma_f32_16x16x32_bf16 v[38:41], v[142:145], v[198:201], v[38:41]
	v_mfma_f32_16x16x32_bf16 v[30:33], v[134:137], v[206:209], v[30:33]
	v_mfma_f32_16x16x32_bf16 v[22:25], v[142:145], v[206:209], v[22:25]
	v_mfma_f32_16x16x32_bf16 v[14:17], v[134:137], v[222:225], v[14:17]
	v_mfma_f32_16x16x32_bf16 v[6:9], v[142:145], v[222:225], v[6:9]
	v_mfma_f32_16x16x32_bf16 v[58:61], v[146:149], v[186:189], v[58:61]
	v_mfma_f32_16x16x32_bf16 v[50:53], v[154:157], v[186:189], v[50:53]
	v_mfma_f32_16x16x32_bf16 v[42:45], v[146:149], v[194:197], v[42:45]
	v_mfma_f32_16x16x32_bf16 v[34:37], v[154:157], v[194:197], v[34:37]
	v_mfma_f32_16x16x32_bf16 v[26:29], v[146:149], v[202:205], v[26:29]
	v_mfma_f32_16x16x32_bf16 v[18:21], v[154:157], v[202:205], v[18:21]
	v_mfma_f32_16x16x32_bf16 v[10:13], v[146:149], v[218:221], v[10:13]
	v_mfma_f32_16x16x32_bf16 v[2:5], v[154:157], v[218:221], v[2:5]
	v_mfma_f32_16x16x32_bf16 v[58:61], v[150:153], v[190:193], v[58:61]
	v_mfma_f32_16x16x32_bf16 v[50:53], v[182:185], v[190:193], v[50:53]
	v_mfma_f32_16x16x32_bf16 v[42:45], v[150:153], v[198:201], v[42:45]
	v_mfma_f32_16x16x32_bf16 v[34:37], v[182:185], v[198:201], v[34:37]
	v_mfma_f32_16x16x32_bf16 v[26:29], v[150:153], v[206:209], v[26:29]
	v_mfma_f32_16x16x32_bf16 v[18:21], v[182:185], v[206:209], v[18:21]
	v_mfma_f32_16x16x32_bf16 v[10:13], v[150:153], v[222:225], v[10:13]
	v_mfma_f32_16x16x32_bf16 v[2:5], v[182:185], v[222:225], v[2:5]
	s_setprio 0
	s_barrier
	s_add_u32 s0, s0, 0x100
	s_addc_u32 s1, s1, 0
	s_add_u32 s5, s5, 0x100
	s_addc_u32 s16, s16, 0
	s_cmp_ge_i32 s27, s84
	s_mov_b32 s17, s27
	s_cbranch_scc0 .LBB0_177
	s_and_b64 vcc, exec, s[74:75]
	s_cbranch_vccz .LBB0_180

; template <int MODE, bool NOMAX = false> ...
;     ...
;                     float sacc = 0.f;
; #pragma unroll
;                     for (int r = 0; r < 16; ++r) { p0[r] = __builtin_amdgcn_exp2f(p0[r]); p1[r] = __builtin_amdgcn_exp2f(p1[r]); sacc += p0[r] + p1[r]; }
;                     l_reg += sacc;
.LBB0_1077:
	v_pk_add_f32 v[182:183], v[182:183], v[178:179]
	v_pk_add_f32 v[166:167], v[166:167], v[184:185]
	v_pk_add_f32 v[180:181], v[180:181], v[176:177]
	v_pk_add_f32 v[98:99], v[98:99], v[96:97]
	v_pk_add_f32 v[12:13], v[12:13], v[14:15]
	v_pk_add_f32 v[8:9], v[8:9], v[10:11]
	v_pk_add_f32 v[4:5], v[4:5], v[6:7]
	v_pk_add_f32 v[182:183], v[182:183], v[166:167]
	v_pk_add_f32 v[180:181], v[180:181], v[98:99]
	v_pk_add_f32 v[12:13], v[12:13], v[8:9]
	v_pk_add_f32 v[4:5], v[4:5], v[2:3]
	v_pk_add_f32 v[182:183], v[182:183], v[180:181]
	v_pk_add_f32 v[12:13], v[12:13], v[4:5]
	v_pk_add_f32 v[182:183], v[182:183], v[12:13]
	v_add_f32_e32 v1, v1, v100
	v_add_f32_e32 v1, v1, v182
	v_add_f32_e32 v1, v1, v183
	v_add_f32_e32 v208, v208, v1

; template <int MODE, bool NOMAX = false> ...
;     ...
;                     float sacc = 0.f;
; #pragma unroll
;                     for (int r = 0; r < 16; ++r) { p0[r] = __builtin_amdgcn_exp2f(p0[r]); p1[r] = __builtin_amdgcn_exp2f(p1[r]); sacc += p0[r] + p1[r]; }
;                     l_reg += sacc;
.LBB0_1100:
	v_pk_add_f32 v[150:151], v[150:151], v[126:127]
	v_pk_add_f32 v[122:123], v[122:123], v[152:153]
	v_pk_add_f32 v[148:149], v[148:149], v[124:125]
	v_pk_add_f32 v[98:99], v[98:99], v[96:97]
	v_pk_add_f32 v[12:13], v[12:13], v[14:15]
	v_pk_add_f32 v[8:9], v[8:9], v[10:11]
	v_pk_add_f32 v[4:5], v[4:5], v[6:7]
	v_pk_add_f32 v[150:151], v[150:151], v[122:123]
	v_pk_add_f32 v[148:149], v[148:149], v[98:99]
	v_pk_add_f32 v[12:13], v[12:13], v[8:9]
	v_pk_add_f32 v[4:5], v[4:5], v[2:3]
	v_pk_add_f32 v[150:151], v[150:151], v[148:149]
	v_pk_add_f32 v[12:13], v[12:13], v[4:5]
	v_pk_add_f32 v[150:151], v[150:151], v[12:13]
	v_add_f32_e32 v1, v1, v100
	v_add_f32_e32 v1, v1, v150
	v_add_f32_e32 v1, v1, v151
	v_add_f32_e32 v158, v158, v1
